# DPP row-reduce for wave_sum in the final RMSNorm loop: 6 ds_bpermute round trips per row -> 4 DPP adds + permlane16/32 swaps
# baseline (speedup 1.0000x reference)
; __device__ __forceinline__ float bflo(unsigned u) { return __uint_as_float(u << 16); }
; __device__ __forceinline__ float bfhi(unsigned u) { return __uint_as_float(u & 0xffff0000u); }
; __device__ __forceinline__ float wave_sum(float v) {
; #pragma unroll
;     for (int o = 1; o < 64; o <<= 1) v += __shfl_xor(v, o);
;     return v;
; }
; __global__ void __launch_bounds__(512, 2) mk_fwd(Args a) {
;     ...
;             for (int row = gw; row < T; row += NGW) {
;                 f32x4* xr = (f32x4*)(X + (size_t)row * DM) + lane; const u32x2* xb = (const u32x2*)(HB + (size_t)row * DM) + lane; f32x4 v[4]; float s = 0.f;
; #pragma unroll
;                 for (int j = 0; j < 4; ++j) { const u32x2 w = xb[64 * j]; v[j] = (f32x4){bflo(w.x), bfhi(w.x), bflo(w.y), bfhi(w.y)}; s += (v[j].x * v[j].x + v[j].y * v[j].y) + (v[j].z * v[j].z + v[j].w * v[j].w); }
;                 const float rs = rsqrtf(wave_sum(s) * (1.0f / DM) + EPS);
; #pragma unroll
;                 for (int j = 0; j < 4; ++j) { const f32x4 g4 = ((const f32x4*)gf)[lane + 64 * j]; xr[64 * j] = v[j] * rs * g4; }
;             }
.LBB0_28:
	flat_load_dwordx2 v[18:19], v[4:5]
	flat_load_dwordx2 v[20:21], v[4:5] offset:512
	flat_load_dwordx2 v[22:23], v[4:5] offset:1024
	flat_load_dwordx2 v[24:25], v[4:5] offset:1536
	s_add_i32 s2, s2, s96
	v_lshl_add_u64 v[4:5], v[4:5], 0, s[8:9]
	s_cmpk_gt_i32 s2, 0x7fff
	s_waitcnt vmcnt(0) lgkmcnt(0)
	v_lshlrev_b32_e32 v26, 16, v18
	v_and_b32_e32 v27, 0xffff0000, v18
	v_lshlrev_b32_e32 v18, 16, v19
	v_and_b32_e32 v19, 0xffff0000, v19
	v_lshlrev_b32_e32 v29, 16, v21
	v_lshlrev_b32_e32 v28, 16, v20
	v_and_b32_e32 v21, 0xffff0000, v21
	v_and_b32_e32 v20, 0xffff0000, v20
	v_lshlrev_b32_e32 v30, 16, v22
	v_and_b32_e32 v31, 0xffff0000, v22
	v_lshlrev_b32_e32 v22, 16, v23
	v_and_b32_e32 v23, 0xffff0000, v23
	v_lshlrev_b32_e32 v33, 16, v24
	v_mul_f32_e32 v0, v19, v19
	v_mul_f32_e32 v32, v27, v27
	v_pk_mul_f32 v[36:37], v[20:21], v[20:21]
	v_mov_b32_e32 v39, v33
	v_mul_f32_e32 v38, v23, v23
	v_pk_fma_f32 v[40:41], v[18:19], v[18:19], v[0:1] op_sel_hi:[1,1,0]
	v_pk_fma_f32 v[42:43], v[26:27], v[26:27], v[32:33] op_sel_hi:[1,1,0]
	v_and_b32_e32 v35, 0xffff0000, v24
	v_lshlrev_b32_e32 v24, 16, v25
	v_and_b32_e32 v25, 0xffff0000, v25
	v_mul_f32_e32 v34, v31, v31
	v_pk_fma_f32 v[36:37], v[28:29], v[28:29], v[36:37]
	v_pk_fma_f32 v[46:47], v[22:23], v[22:23], v[38:39] op_sel_hi:[1,1,0]
	v_mov_b32_e32 v32, v42
	v_mov_b32_e32 v38, v40
	v_mul_f32_e32 v48, v35, v35
	v_mul_f32_e32 v49, v24, v24
	v_mul_f32_e32 v50, v25, v25
	v_pk_fma_f32 v[44:45], v[30:31], v[30:31], v[34:35] op_sel_hi:[1,1,0]
	v_pk_add_f32 v[40:41], v[42:43], v[40:41]
	v_pk_add_f32 v[36:37], v[36:37], v[36:37] op_sel:[0,1] op_sel_hi:[1,0]
	v_pk_mul_f32 v[38:39], v[32:33], v[38:39]
	v_mov_b32_e32 v45, v49
	v_mov_b32_e32 v47, v50
	v_mov_b32_e32 v37, v48
	v_mov_b32_e32 v41, v39
	v_pk_add_f32 v[42:43], v[44:45], v[46:47]
	v_pk_add_f32 v[36:37], v[40:41], v[36:37]
	v_mov_b32_e32 v34, v33
	v_pk_add_f32 v[36:37], v[36:37], v[42:43]
	s_nop 0
	v_add_f32_e32 v0, v36, v37
	s_nop 1
	v_add_f32_dpp v0, v0, v0 quad_perm:[1,0,3,2] row_mask:0xf bank_mask:0xf
	s_nop 1
	v_add_f32_dpp v0, v0, v0 quad_perm:[2,3,0,1] row_mask:0xf bank_mask:0xf
	s_nop 1
	v_add_f32_dpp v0, v0, v0 row_half_mirror row_mask:0xf bank_mask:0xf
	s_nop 1
	v_add_f32_dpp v0, v0, v0 row_mirror row_mask:0xf bank_mask:0xf
	v_mov_b32_e32 v32, v0
	s_nop 1
	v_permlane16_swap_b32_e32 v32, v0
	v_add_f32_e32 v0, v0, v32
	v_mov_b32_e32 v32, v0
	s_nop 1
	v_permlane32_swap_b32_e32 v32, v0
	v_add_f32_e32 v0, v0, v32
	v_fmamk_f32 v0, v0, 0x3a800000, v205
	v_mul_f32_e32 v32, 0x4b800000, v0
	v_cmp_gt_f32_e32 vcc, s77, v0
	s_nop 1
	v_cndmask_b32_e32 v0, v0, v32, vcc
	v_rsq_f32_e32 v0, v0
	s_nop 0
	v_mul_f32_e32 v32, 0x45800000, v0
	v_cndmask_b32_e32 v0, v0, v32, vcc
	v_pk_mul_f32 v[26:27], v[0:1], v[26:27] op_sel_hi:[0,1]
	v_pk_mul_f32 v[18:19], v[0:1], v[18:19] op_sel_hi:[0,1]
	v_pk_mul_f32 v[16:17], v[18:19], v[54:55]
	v_pk_mul_f32 v[14:15], v[26:27], v[52:53]
	flat_store_dwordx4 v[6:7], v[14:17]
	v_mov_b32_e32 v18, v29
	v_mov_b32_e32 v19, v21
	v_mov_b32_e32 v29, v20
	v_pk_mul_f32 v[18:19], v[0:1], v[18:19] op_sel_hi:[0,1]
	v_pk_mul_f32 v[20:21], v[0:1], v[28:29] op_sel_hi:[0,1]
	v_pk_mul_f32 v[14:15], v[20:21], v[56:57]
	v_pk_mul_f32 v[16:17], v[18:19], v[58:59]
	flat_store_dwordx4 v[6:7], v[14:17] offset:1024
	v_pk_mul_f32 v[18:19], v[0:1], v[22:23] op_sel_hi:[0,1]
	v_pk_mul_f32 v[20:21], v[0:1], v[30:31] op_sel_hi:[0,1]
	v_pk_mul_f32 v[14:15], v[20:21], v[60:61]
	v_pk_mul_f32 v[16:17], v[18:19], v[62:63]
	flat_store_dwordx4 v[6:7], v[14:17] offset:2048
	v_pk_mul_f32 v[18:19], v[0:1], v[24:25] op_sel_hi:[0,1]
	v_pk_mul_f32 v[20:21], v[0:1], v[34:35] op_sel_hi:[0,1]
	v_pk_mul_f32 v[14:15], v[20:21], v[64:65]
	v_pk_mul_f32 v[16:17], v[18:19], v[66:67]
	flat_store_dwordx4 v[6:7], v[14:17] offset:3072
	v_lshl_add_u64 v[6:7], v[6:7], 0, s[6:7]
	s_cbranch_scc0 .LBB0_28
